# mixers row-rstd pre-pass: loads for 4 rows issued together per loop trip, counted vmcnt per row
# baseline (speedup 1.0000x reference)
; DI float bflo(unsigned v) { return __uint_as_float(v << 16); }
; DI float bfhi(unsigned v) { return __uint_as_float(v & 0xffff0000u); }
; DI float wave_sum(float v) { return row_sum16(xadd16(xadd32(v))); }
; DI void phase_mixers(const Params& p, int l, LAS char* lds) {
;     ...
;         for (int row = blockIdx.x * 4 + wv; row < MTOK; row += gridDim.x * 4) {
;             const u32x2 a = *(const u32x2*)(zmr + (size_t)row * 1024 + ln * 4);
;             const unsigned b = *(const unsigned*)(zmr + (size_t)row * 1024 + 256 + ln * 2);
;             float sq = bflo(a[0]) * bflo(a[0]) + bfhi(a[0]) * bfhi(a[0]) + bflo(a[1]) * bflo(a[1]) + bfhi(a[1]) * bfhi(a[1]);
;             float sk = bflo(b) * bflo(b) + bfhi(b) * bfhi(b);
;             sq = wave_sum(sq); sk = wave_sum(sk);
;             if (ln == 0) *(f32x2*)(rsb + (size_t)row * 2) = (f32x2){rsqrtf(sq * (1.f / 256.f) + EPS), rsqrtf(sk * (1.f / 128.f) + EPS)};
;         }
.LBB0_142:
	s_and_b64 vcc, exec, s[38:39]
	s_cbranch_vccz .LBB0_356
	v_mov_b32_e32 v102, v151
	v_readlane_b32 s0, v229, 42
	v_ashrrev_i32_e32 v101, 6, v102
	v_and_b32_e32 v114, 63, v102
	v_add_u32_e32 v2, s0, v101
	s_mov_b32 s0, 0x8080
	v_cmp_gt_i32_e32 vcc, s0, v2
	v_lshlrev_b32_e32 v100, 2, v114
	s_and_saveexec_b64 s[42:43], vcc
	v_readlane_b32 s8, v231, 2
	v_readlane_b32 s4, v231, 4
	s_mov_b32 s10, 0x3b800000
	v_readlane_b32 s9, v231, 3
	v_readlane_b32 s5, v231, 5
	s_movk_i32 s6, 0x1000
	s_brev_b32 s11, 60
	s_mov_b32 s7, 0x807f
	s_cbranch_execz .LBB0_148
	v_lshlrev_b32_e32 v4, 1, v114
	v_cmp_eq_u32_e32 vcc, 0, v114
	s_mov_b64 s[44:45], 0
	v_lshlrev_b32_e32 v148, 1, v100
	v_lshlrev_b32_e32 v4, 1, v4
	v_readfirstlane_b32 s44, v2
	v_mov_b32_e32 v3, 0
	s_nop 3
	s_mov_b32 s33, s44
	s_mov_b32 s34, 4
.Lrs_loop:
	s_lshl_b32 s38, s33, 11
	s_add_u32 s40, s18, s38
	s_addc_u32 s41, s19, 0
	global_load_dwordx2 v[12:13], v148, s[40:41]
	global_load_dword v46, v4, s[40:41] offset:512
	s_add_i32 s33, s33, s24
	s_lshl_b32 s38, s33, 11
	s_add_u32 s40, s18, s38
	s_addc_u32 s41, s19, 0
	global_load_dwordx2 v[14:15], v148, s[40:41]
	global_load_dword v47, v4, s[40:41] offset:512
	s_add_i32 s33, s33, s24
	s_lshl_b32 s38, s33, 11
	s_add_u32 s40, s18, s38
	s_addc_u32 s41, s19, 0
	global_load_dwordx2 v[16:17], v148, s[40:41]
	global_load_dword v48, v4, s[40:41] offset:512
	s_add_i32 s33, s33, s24
	s_lshl_b32 s38, s33, 11
	s_add_u32 s40, s18, s38
	s_addc_u32 s41, s19, 0
	global_load_dwordx2 v[18:19], v148, s[40:41]
	global_load_dword v49, v4, s[40:41] offset:512
	s_add_i32 s33, s33, s24
	s_waitcnt vmcnt(6)
	v_mov_b32_e32 v8, v12
	v_mov_b32_e32 v9, v13
	v_mov_b32_e32 v1, v46
	v_and_b32_e32 v7, 0xffff0000, v8
	v_lshlrev_b32_e32 v6, 16, v8
	v_mul_f32_e32 v8, v7, v7
	v_pk_fma_f32 v[6:7], v[6:7], v[6:7], v[8:9] op_sel_hi:[1,1,0]
	v_and_b32_e32 v8, 0xffff0000, v9
	v_lshlrev_b32_e32 v9, 16, v9
	v_mul_f32_e32 v10, v9, v9
	v_pk_add_f32 v[6:7], v[10:11], v[6:7] op_sel_hi:[0,1]
	v_pk_fma_f32 v[6:7], v[8:9], v[8:9], v[6:7]
	v_and_b32_e32 v9, 0xffff0000, v1
	v_lshlrev_b32_e32 v8, 16, v1
	v_mul_f32_e32 v10, v9, v9
	v_mov_b32_e32 v1, v6
	v_pk_fma_f32 v[8:9], v[8:9], v[8:9], v[10:11] op_sel_hi:[1,1,0]
	s_nop 0
	v_permlane32_swap_b32_e32 v6, v1
	v_add_f32_e32 v6, v6, v1
	v_mov_b32_e32 v1, v8
	s_nop 1
	v_permlane32_swap_b32_e32 v8, v1
	v_add_f32_e32 v7, v8, v1
	v_mov_b32_e32 v10, v6
	v_mov_b32_e32 v11, v7
	s_nop 0
	v_permlane16_swap_b32_e32 v6, v10
	v_permlane16_swap_b32_e32 v7, v11
	v_pk_add_f32 v[6:7], v[6:7], v[10:11]
	s_nop 1
	v_mov_b32_dpp v8, v6 row_ror:8 row_mask:0xf bank_mask:0xf bound_ctrl:1
	v_mov_b32_dpp v9, v7 row_ror:8 row_mask:0xf bank_mask:0xf bound_ctrl:1
	v_pk_add_f32 v[6:7], v[6:7], v[8:9]
	s_nop 1
	v_mov_b32_dpp v8, v6 row_ror:4 row_mask:0xf bank_mask:0xf bound_ctrl:1
	v_mov_b32_dpp v9, v7 row_ror:4 row_mask:0xf bank_mask:0xf bound_ctrl:1
	v_pk_add_f32 v[6:7], v[6:7], v[8:9]
	s_nop 1
	v_mov_b32_dpp v8, v6 quad_perm:[2,3,0,1] row_mask:0xf bank_mask:0xf bound_ctrl:1
	v_mov_b32_dpp v9, v7 quad_perm:[2,3,0,1] row_mask:0xf bank_mask:0xf bound_ctrl:1
	v_pk_add_f32 v[6:7], v[6:7], v[8:9]
	s_nop 1
	v_mov_b32_dpp v8, v6 quad_perm:[1,0,3,2] row_mask:0xf bank_mask:0xf bound_ctrl:1
	v_mov_b32_dpp v9, v7 quad_perm:[1,0,3,2] row_mask:0xf bank_mask:0xf bound_ctrl:1
	s_and_saveexec_b64 s[46:47], vcc
	v_pk_add_f32 v[6:7], v[6:7], v[8:9]
	s_mov_b32 s0, 0x800000
	v_pk_fma_f32 v[6:7], v[6:7], s[10:11], v[150:151] op_sel_hi:[1,1,0]
	s_nop 0
	v_mul_f32_e32 v1, 0x4b800000, v6
	v_cmp_gt_f32_e64 s[38:39], s0, v6
	v_cmp_gt_f32_e64 s[40:41], s0, v7
	s_mov_b32 s0, 0x45800000
	v_cndmask_b32_e64 v1, v6, v1, s[38:39]
	v_rsq_f32_e32 v6, v1
	v_mul_f32_e32 v1, 0x4b800000, v7
	v_cndmask_b32_e64 v1, v7, v1, s[40:41]
	v_rsq_f32_e32 v7, v1
	s_nop 0
	v_pk_mul_f32 v[8:9], v[6:7], s[0:1] op_sel_hi:[1,0]
	s_nop 0
	v_cndmask_b32_e64 v7, v7, v9, s[40:41]
	v_cndmask_b32_e64 v6, v6, v8, s[38:39]
	v_lshl_add_u64 v[8:9], v[2:3], 3, s[4:5]
	global_store_dwordx2 v[8:9], v[6:7], off
	s_or_b64 exec, exec, s[46:47]
	v_add_u32_e32 v2, s24, v2
	s_waitcnt vmcnt(5)
	v_mov_b32_e32 v8, v14
	v_mov_b32_e32 v9, v15
	v_mov_b32_e32 v1, v47
	v_and_b32_e32 v7, 0xffff0000, v8
	v_lshlrev_b32_e32 v6, 16, v8
	v_mul_f32_e32 v8, v7, v7
	v_pk_fma_f32 v[6:7], v[6:7], v[6:7], v[8:9] op_sel_hi:[1,1,0]
	v_and_b32_e32 v8, 0xffff0000, v9
	v_lshlrev_b32_e32 v9, 16, v9
	v_mul_f32_e32 v10, v9, v9
	v_pk_add_f32 v[6:7], v[10:11], v[6:7] op_sel_hi:[0,1]
	v_pk_fma_f32 v[6:7], v[8:9], v[8:9], v[6:7]
	v_and_b32_e32 v9, 0xffff0000, v1
	v_lshlrev_b32_e32 v8, 16, v1
	v_mul_f32_e32 v10, v9, v9
	v_mov_b32_e32 v1, v6
	v_pk_fma_f32 v[8:9], v[8:9], v[8:9], v[10:11] op_sel_hi:[1,1,0]
	s_nop 0
	v_permlane32_swap_b32_e32 v6, v1
	v_add_f32_e32 v6, v6, v1
	v_mov_b32_e32 v1, v8
	s_nop 1
	v_permlane32_swap_b32_e32 v8, v1
	v_add_f32_e32 v7, v8, v1
	v_mov_b32_e32 v10, v6
	v_mov_b32_e32 v11, v7
	s_nop 0
	v_permlane16_swap_b32_e32 v6, v10
	v_permlane16_swap_b32_e32 v7, v11
	v_pk_add_f32 v[6:7], v[6:7], v[10:11]
	s_nop 1
	v_mov_b32_dpp v8, v6 row_ror:8 row_mask:0xf bank_mask:0xf bound_ctrl:1
	v_mov_b32_dpp v9, v7 row_ror:8 row_mask:0xf bank_mask:0xf bound_ctrl:1
	v_pk_add_f32 v[6:7], v[6:7], v[8:9]
	s_nop 1
	v_mov_b32_dpp v8, v6 row_ror:4 row_mask:0xf bank_mask:0xf bound_ctrl:1
	v_mov_b32_dpp v9, v7 row_ror:4 row_mask:0xf bank_mask:0xf bound_ctrl:1
	v_pk_add_f32 v[6:7], v[6:7], v[8:9]
	s_nop 1
	v_mov_b32_dpp v8, v6 quad_perm:[2,3,0,1] row_mask:0xf bank_mask:0xf bound_ctrl:1
	v_mov_b32_dpp v9, v7 quad_perm:[2,3,0,1] row_mask:0xf bank_mask:0xf bound_ctrl:1
	v_pk_add_f32 v[6:7], v[6:7], v[8:9]
	s_nop 1
	v_mov_b32_dpp v8, v6 quad_perm:[1,0,3,2] row_mask:0xf bank_mask:0xf bound_ctrl:1
	v_mov_b32_dpp v9, v7 quad_perm:[1,0,3,2] row_mask:0xf bank_mask:0xf bound_ctrl:1
	s_and_saveexec_b64 s[46:47], vcc
	v_pk_add_f32 v[6:7], v[6:7], v[8:9]
	s_mov_b32 s0, 0x800000
	v_pk_fma_f32 v[6:7], v[6:7], s[10:11], v[150:151] op_sel_hi:[1,1,0]
	s_nop 0
	v_mul_f32_e32 v1, 0x4b800000, v6
	v_cmp_gt_f32_e64 s[38:39], s0, v6
	v_cmp_gt_f32_e64 s[40:41], s0, v7
	s_mov_b32 s0, 0x45800000
	v_cndmask_b32_e64 v1, v6, v1, s[38:39]
	v_rsq_f32_e32 v6, v1
	v_mul_f32_e32 v1, 0x4b800000, v7
	v_cndmask_b32_e64 v1, v7, v1, s[40:41]
	v_rsq_f32_e32 v7, v1
	s_nop 0
	v_pk_mul_f32 v[8:9], v[6:7], s[0:1] op_sel_hi:[1,0]
	s_nop 0
	v_cndmask_b32_e64 v7, v7, v9, s[40:41]
	v_cndmask_b32_e64 v6, v6, v8, s[38:39]
	v_lshl_add_u64 v[8:9], v[2:3], 3, s[4:5]
	global_store_dwordx2 v[8:9], v[6:7], off
	s_or_b64 exec, exec, s[46:47]
	v_add_u32_e32 v2, s24, v2
	s_waitcnt vmcnt(4)
; DI float bflo(unsigned v) { return __uint_as_float(v << 16); }
; DI float bfhi(unsigned v) { return __uint_as_float(v & 0xffff0000u); }
; DI float wave_sum(float v) { return row_sum16(xadd16(xadd32(v))); }
; DI void phase_mixers(const Params& p, int l, LAS char* lds) {
;     ...
;         for (int row = blockIdx.x * 4 + wv; row < MTOK; row += gridDim.x * 4) {
;             const u32x2 a = *(const u32x2*)(zmr + (size_t)row * 1024 + ln * 4);
;             const unsigned b = *(const unsigned*)(zmr + (size_t)row * 1024 + 256 + ln * 2);
;             float sq = bflo(a[0]) * bflo(a[0]) + bfhi(a[0]) * bfhi(a[0]) + bflo(a[1]) * bflo(a[1]) + bfhi(a[1]) * bfhi(a[1]);
;             float sk = bflo(b) * bflo(b) + bfhi(b) * bfhi(b);
;             sq = wave_sum(sq); sk = wave_sum(sk);
;             if (ln == 0) *(f32x2*)(rsb + (size_t)row * 2) = (f32x2){rsqrtf(sq * (1.f / 256.f) + EPS), rsqrtf(sk * (1.f / 128.f) + EPS)};
;         }
	v_mov_b32_e32 v8, v16
	v_mov_b32_e32 v9, v17
	v_mov_b32_e32 v1, v48
	v_and_b32_e32 v7, 0xffff0000, v8
	v_lshlrev_b32_e32 v6, 16, v8
	v_mul_f32_e32 v8, v7, v7
	v_pk_fma_f32 v[6:7], v[6:7], v[6:7], v[8:9] op_sel_hi:[1,1,0]
	v_and_b32_e32 v8, 0xffff0000, v9
	v_lshlrev_b32_e32 v9, 16, v9
	v_mul_f32_e32 v10, v9, v9
	v_pk_add_f32 v[6:7], v[10:11], v[6:7] op_sel_hi:[0,1]
	v_pk_fma_f32 v[6:7], v[8:9], v[8:9], v[6:7]
	v_and_b32_e32 v9, 0xffff0000, v1
	v_lshlrev_b32_e32 v8, 16, v1
	v_mul_f32_e32 v10, v9, v9
	v_mov_b32_e32 v1, v6
	v_pk_fma_f32 v[8:9], v[8:9], v[8:9], v[10:11] op_sel_hi:[1,1,0]
	s_nop 0
	v_permlane32_swap_b32_e32 v6, v1
	v_add_f32_e32 v6, v6, v1
	v_mov_b32_e32 v1, v8
	s_nop 1
	v_permlane32_swap_b32_e32 v8, v1
	v_add_f32_e32 v7, v8, v1
	v_mov_b32_e32 v10, v6
	v_mov_b32_e32 v11, v7
	s_nop 0
	v_permlane16_swap_b32_e32 v6, v10
	v_permlane16_swap_b32_e32 v7, v11
	v_pk_add_f32 v[6:7], v[6:7], v[10:11]
	s_nop 1
	v_mov_b32_dpp v8, v6 row_ror:8 row_mask:0xf bank_mask:0xf bound_ctrl:1
	v_mov_b32_dpp v9, v7 row_ror:8 row_mask:0xf bank_mask:0xf bound_ctrl:1
	v_pk_add_f32 v[6:7], v[6:7], v[8:9]
	s_nop 1
	v_mov_b32_dpp v8, v6 row_ror:4 row_mask:0xf bank_mask:0xf bound_ctrl:1
	v_mov_b32_dpp v9, v7 row_ror:4 row_mask:0xf bank_mask:0xf bound_ctrl:1
	v_pk_add_f32 v[6:7], v[6:7], v[8:9]
	s_nop 1
	v_mov_b32_dpp v8, v6 quad_perm:[2,3,0,1] row_mask:0xf bank_mask:0xf bound_ctrl:1
	v_mov_b32_dpp v9, v7 quad_perm:[2,3,0,1] row_mask:0xf bank_mask:0xf bound_ctrl:1
	v_pk_add_f32 v[6:7], v[6:7], v[8:9]
	s_nop 1
	v_mov_b32_dpp v8, v6 quad_perm:[1,0,3,2] row_mask:0xf bank_mask:0xf bound_ctrl:1
	v_mov_b32_dpp v9, v7 quad_perm:[1,0,3,2] row_mask:0xf bank_mask:0xf bound_ctrl:1
	s_and_saveexec_b64 s[46:47], vcc
	v_pk_add_f32 v[6:7], v[6:7], v[8:9]
	s_mov_b32 s0, 0x800000
	v_pk_fma_f32 v[6:7], v[6:7], s[10:11], v[150:151] op_sel_hi:[1,1,0]
	s_nop 0
	v_mul_f32_e32 v1, 0x4b800000, v6
	v_cmp_gt_f32_e64 s[38:39], s0, v6
	v_cmp_gt_f32_e64 s[40:41], s0, v7
	s_mov_b32 s0, 0x45800000
	v_cndmask_b32_e64 v1, v6, v1, s[38:39]
	v_rsq_f32_e32 v6, v1
	v_mul_f32_e32 v1, 0x4b800000, v7
	v_cndmask_b32_e64 v1, v7, v1, s[40:41]
	v_rsq_f32_e32 v7, v1
	s_nop 0
	v_pk_mul_f32 v[8:9], v[6:7], s[0:1] op_sel_hi:[1,0]
	s_nop 0
	v_cndmask_b32_e64 v7, v7, v9, s[40:41]
	v_cndmask_b32_e64 v6, v6, v8, s[38:39]
	v_lshl_add_u64 v[8:9], v[2:3], 3, s[4:5]
	global_store_dwordx2 v[8:9], v[6:7], off
	s_or_b64 exec, exec, s[46:47]
	v_add_u32_e32 v2, s24, v2
	s_waitcnt vmcnt(3)
	v_mov_b32_e32 v8, v18
	v_mov_b32_e32 v9, v19
	v_mov_b32_e32 v1, v49
	v_and_b32_e32 v7, 0xffff0000, v8
	v_lshlrev_b32_e32 v6, 16, v8
	v_mul_f32_e32 v8, v7, v7
	v_pk_fma_f32 v[6:7], v[6:7], v[6:7], v[8:9] op_sel_hi:[1,1,0]
	v_and_b32_e32 v8, 0xffff0000, v9
	v_lshlrev_b32_e32 v9, 16, v9
	v_mul_f32_e32 v10, v9, v9
	v_pk_add_f32 v[6:7], v[10:11], v[6:7] op_sel_hi:[0,1]
	v_pk_fma_f32 v[6:7], v[8:9], v[8:9], v[6:7]
	v_and_b32_e32 v9, 0xffff0000, v1
	v_lshlrev_b32_e32 v8, 16, v1
	v_mul_f32_e32 v10, v9, v9
	v_mov_b32_e32 v1, v6
	v_pk_fma_f32 v[8:9], v[8:9], v[8:9], v[10:11] op_sel_hi:[1,1,0]
	s_nop 0
	v_permlane32_swap_b32_e32 v6, v1
	v_add_f32_e32 v6, v6, v1
	v_mov_b32_e32 v1, v8
	s_nop 1
	v_permlane32_swap_b32_e32 v8, v1
	v_add_f32_e32 v7, v8, v1
	v_mov_b32_e32 v10, v6
	v_mov_b32_e32 v11, v7
	s_nop 0
	v_permlane16_swap_b32_e32 v6, v10
	v_permlane16_swap_b32_e32 v7, v11
	v_pk_add_f32 v[6:7], v[6:7], v[10:11]
	s_nop 1
	v_mov_b32_dpp v8, v6 row_ror:8 row_mask:0xf bank_mask:0xf bound_ctrl:1
	v_mov_b32_dpp v9, v7 row_ror:8 row_mask:0xf bank_mask:0xf bound_ctrl:1
	v_pk_add_f32 v[6:7], v[6:7], v[8:9]
	s_nop 1
	v_mov_b32_dpp v8, v6 row_ror:4 row_mask:0xf bank_mask:0xf bound_ctrl:1
	v_mov_b32_dpp v9, v7 row_ror:4 row_mask:0xf bank_mask:0xf bound_ctrl:1
	v_pk_add_f32 v[6:7], v[6:7], v[8:9]
	s_nop 1
	v_mov_b32_dpp v8, v6 quad_perm:[2,3,0,1] row_mask:0xf bank_mask:0xf bound_ctrl:1
	v_mov_b32_dpp v9, v7 quad_perm:[2,3,0,1] row_mask:0xf bank_mask:0xf bound_ctrl:1
	v_pk_add_f32 v[6:7], v[6:7], v[8:9]
	s_nop 1
	v_mov_b32_dpp v8, v6 quad_perm:[1,0,3,2] row_mask:0xf bank_mask:0xf bound_ctrl:1
	v_mov_b32_dpp v9, v7 quad_perm:[1,0,3,2] row_mask:0xf bank_mask:0xf bound_ctrl:1
	s_and_saveexec_b64 s[46:47], vcc
	v_pk_add_f32 v[6:7], v[6:7], v[8:9]
	s_mov_b32 s0, 0x800000
	v_pk_fma_f32 v[6:7], v[6:7], s[10:11], v[150:151] op_sel_hi:[1,1,0]
	s_nop 0
	v_mul_f32_e32 v1, 0x4b800000, v6
	v_cmp_gt_f32_e64 s[38:39], s0, v6
	v_cmp_gt_f32_e64 s[40:41], s0, v7
	s_mov_b32 s0, 0x45800000
	v_cndmask_b32_e64 v1, v6, v1, s[38:39]
	v_rsq_f32_e32 v6, v1
	v_mul_f32_e32 v1, 0x4b800000, v7
	v_cndmask_b32_e64 v1, v7, v1, s[40:41]
	v_rsq_f32_e32 v7, v1
	s_nop 0
	v_pk_mul_f32 v[8:9], v[6:7], s[0:1] op_sel_hi:[1,0]
	s_nop 0
	v_cndmask_b32_e64 v7, v7, v9, s[40:41]
	v_cndmask_b32_e64 v6, v6, v8, s[38:39]
	v_lshl_add_u64 v[8:9], v[2:3], 3, s[4:5]
	global_store_dwordx2 v[8:9], v[6:7], off
	s_or_b64 exec, exec, s[46:47]
	v_add_u32_e32 v2, s24, v2
	s_add_i32 s34, s34, -1
	s_cmp_lg_u32 s34, 0
	s_cbranch_scc1 .Lrs_loop
; DI float bflo(unsigned v) { return __uint_as_float(v << 16); }
; DI float bfhi(unsigned v) { return __uint_as_float(v & 0xffff0000u); }
; DI float wave_sum(float v) { return row_sum16(xadd16(xadd32(v))); }
; DI int vblock() { const int G = gridDim.x; return (G & 7) ? (int)blockIdx.x : (int)((blockIdx.x & 7) * (G >> 3) + (blockIdx.x >> 3)); }
; DI void phase_mixers(const Params& p, int l, LAS char* lds) {
;     ...
;         for (int row = blockIdx.x * 4 + wv; row < MTOK; row += gridDim.x * 4) {
;             const u32x2 a = *(const u32x2*)(zmr + (size_t)row * 1024 + ln * 4);
;             const unsigned b = *(const unsigned*)(zmr + (size_t)row * 1024 + 256 + ln * 2);
;             float sq = bflo(a[0]) * bflo(a[0]) + bfhi(a[0]) * bfhi(a[0]) + bflo(a[1]) * bflo(a[1]) + bfhi(a[1]) * bfhi(a[1]);
;             float sk = bflo(b) * bflo(b) + bfhi(b) * bfhi(b);
;             sq = wave_sum(sq); sk = wave_sum(sk);
;             if (ln == 0) *(f32x2*)(rsb + (size_t)row * 2) = (f32x2){rsqrtf(sq * (1.f / 256.f) + EPS), rsqrtf(sk * (1.f / 128.f) + EPS)};
;         }
	s_cmp_gt_u32 s44, 0x7f
	s_cbranch_scc1 .Lrs_done
	s_lshl_b32 s38, s33, 11
	s_add_u32 s40, s18, s38
	s_addc_u32 s41, s19, 0
	global_load_dwordx2 v[12:13], v148, s[40:41]
	global_load_dword v46, v4, s[40:41] offset:512
	s_add_i32 s33, s33, s24
	s_waitcnt vmcnt(0)
	v_mov_b32_e32 v8, v12
	v_mov_b32_e32 v9, v13
	v_mov_b32_e32 v1, v46
	v_and_b32_e32 v7, 0xffff0000, v8
	v_lshlrev_b32_e32 v6, 16, v8
	v_mul_f32_e32 v8, v7, v7
	v_pk_fma_f32 v[6:7], v[6:7], v[6:7], v[8:9] op_sel_hi:[1,1,0]
	v_and_b32_e32 v8, 0xffff0000, v9
	v_lshlrev_b32_e32 v9, 16, v9
	v_mul_f32_e32 v10, v9, v9
	v_pk_add_f32 v[6:7], v[10:11], v[6:7] op_sel_hi:[0,1]
	v_pk_fma_f32 v[6:7], v[8:9], v[8:9], v[6:7]
	v_and_b32_e32 v9, 0xffff0000, v1
	v_lshlrev_b32_e32 v8, 16, v1
	v_mul_f32_e32 v10, v9, v9
	v_mov_b32_e32 v1, v6
	v_pk_fma_f32 v[8:9], v[8:9], v[8:9], v[10:11] op_sel_hi:[1,1,0]
	s_nop 0
	v_permlane32_swap_b32_e32 v6, v1
	v_add_f32_e32 v6, v6, v1
	v_mov_b32_e32 v1, v8
	s_nop 1
	v_permlane32_swap_b32_e32 v8, v1
	v_add_f32_e32 v7, v8, v1
	v_mov_b32_e32 v10, v6
	v_mov_b32_e32 v11, v7
	s_nop 0
	v_permlane16_swap_b32_e32 v6, v10
	v_permlane16_swap_b32_e32 v7, v11
	v_pk_add_f32 v[6:7], v[6:7], v[10:11]
	s_nop 1
	v_mov_b32_dpp v8, v6 row_ror:8 row_mask:0xf bank_mask:0xf bound_ctrl:1
	v_mov_b32_dpp v9, v7 row_ror:8 row_mask:0xf bank_mask:0xf bound_ctrl:1
	v_pk_add_f32 v[6:7], v[6:7], v[8:9]
	s_nop 1
	v_mov_b32_dpp v8, v6 row_ror:4 row_mask:0xf bank_mask:0xf bound_ctrl:1
	v_mov_b32_dpp v9, v7 row_ror:4 row_mask:0xf bank_mask:0xf bound_ctrl:1
	v_pk_add_f32 v[6:7], v[6:7], v[8:9]
	s_nop 1
	v_mov_b32_dpp v8, v6 quad_perm:[2,3,0,1] row_mask:0xf bank_mask:0xf bound_ctrl:1
	v_mov_b32_dpp v9, v7 quad_perm:[2,3,0,1] row_mask:0xf bank_mask:0xf bound_ctrl:1
	v_pk_add_f32 v[6:7], v[6:7], v[8:9]
	s_nop 1
	v_mov_b32_dpp v8, v6 quad_perm:[1,0,3,2] row_mask:0xf bank_mask:0xf bound_ctrl:1
	v_mov_b32_dpp v9, v7 quad_perm:[1,0,3,2] row_mask:0xf bank_mask:0xf bound_ctrl:1
	s_and_saveexec_b64 s[46:47], vcc
	v_pk_add_f32 v[6:7], v[6:7], v[8:9]
	s_mov_b32 s0, 0x800000
	v_pk_fma_f32 v[6:7], v[6:7], s[10:11], v[150:151] op_sel_hi:[1,1,0]
	s_nop 0
	v_mul_f32_e32 v1, 0x4b800000, v6
	v_cmp_gt_f32_e64 s[38:39], s0, v6
	v_cmp_gt_f32_e64 s[40:41], s0, v7
	s_mov_b32 s0, 0x45800000
	v_cndmask_b32_e64 v1, v6, v1, s[38:39]
	v_rsq_f32_e32 v6, v1
	v_mul_f32_e32 v1, 0x4b800000, v7
	v_cndmask_b32_e64 v1, v7, v1, s[40:41]
	v_rsq_f32_e32 v7, v1
	s_nop 0
	v_pk_mul_f32 v[8:9], v[6:7], s[0:1] op_sel_hi:[1,0]
	s_nop 0
	v_cndmask_b32_e64 v7, v7, v9, s[40:41]
	v_cndmask_b32_e64 v6, v6, v8, s[38:39]
	v_lshl_add_u64 v[8:9], v[2:3], 3, s[4:5]
	global_store_dwordx2 v[8:9], v[6:7], off
	s_or_b64 exec, exec, s[46:47]
	v_add_u32_e32 v2, s24, v2
.Lrs_done:
.LBB0_148:
	s_or_b64 exec, exec, s[42:43]
	s_load_dword s0, s[14:15], 0x10
	s_load_dword s4, s[14:15], 0x0
	s_movk_i32 s33, 0xa00
	s_mov_b32 s10, 0x800000
	s_movk_i32 s11, 0x1200
	s_waitcnt lgkmcnt(0)
	s_lshr_b32 s0, s0, 16
	s_cmp_lg_u32 s0, 0
	s_cselect_b64 s[0:1], -1, 0
	s_cmp_lg_u64 s[0:1], 0
	s_addc_u32 s3, s4, 0
	s_and_b32 s0, s3, 7
	s_cmp_eq_u32 s0, 0
	s_cselect_b64 s[40:41], -1, 0
	s_cmp_lg_u32 s0, 0
	s_mov_b32 s1, s2
	s_cbranch_scc1 .LBB0_150
	s_ashr_i32 s0, s3, 3
	v_readlane_b32 s1, v231, 0
	s_mul_i32 s0, s0, s1
	v_readlane_b32 s1, v231, 1
	s_add_i32 s1, s0, s1
